# lru sample tiles: the four initial recurrent states requested once at the start of the tile's iteration into spare registers; 3a and the next iteration's deferred scan read them from there
# baseline (speedup 1.0000x reference)
; #define LAS __attribute__((address_space(3)))
; __device__ __forceinline__ float bflo(unsigned w) { return __uint_as_float(w << 16); }
; __device__ __forceinline__ float bfhi(unsigned w) { return __uint_as_float(w & 0xffff0000u); }
; __device__ __forceinline__ u32x4 pack8(f32x4 a, f32x4 b) { u32x4 w; w.x = cvtpk(a[0], a[1]); w.y = cvtpk(a[2], a[3]); w.z = cvtpk(b[0], b[1]); w.w = cvtpk(b[2], b[3]); return w; }
; template <int MODE> __device__ __forceinline__ void lru_phase(const Params& P, LAS unsigned char* lds, int l, int tid_in) {
;     ...
; #pragma unroll
;             for (int j = 0; j < 2; ++j) {
;                 f32x4 a0 = *(const LAS f32x4*)(cwl + 512 + c8 * 8), a1 = *(const LAS f32x4*)(cwl + 512 + c8 * 8 + 4);
; #pragma unroll
;                 for (int i = 0; i < 4; ++i) { const u32x4 xw = xr[j][i]; f32x4 x0, x1; const f32x4 w0 = *(const LAS f32x4*)(cwl + i * 128 + c8 * 8), w1 = *(const LAS f32x4*)(cwl + i * 128 + c8 * 8 + 4);
;                     x0[0] = bflo(xw.x); x0[1] = bfhi(xw.x); x0[2] = bflo(xw.y); x0[3] = bfhi(xw.y); x1[0] = bflo(xw.z); x1[1] = bfhi(xw.z); x1[2] = bflo(xw.w); x1[3] = bfhi(xw.w);
;                     a0 += w0 * x0; a1 += w1 * x1; }
;                 *(LAS u32x4*)(xcb + (r0 + 32 * j) * 136 + c8 * 8) = pack8(a0, a1);
;             }
;             if (tile + tstride < NTILE64) lru_load_rows(P, l, tile + tstride, r0, c0, xr);
;     ...
;             for (int i = 0; i < 16; ++i) {
;                 const float a2 = sa[(16 * q + i) * 128 + cs], b2 = sb[(16 * q + i) * 128 + cs];
;                 const bool reset = samp ? ((i & 3) == 0) : (i == rs);
;                 float h0 = 0.f; if (samp && reset) h0 = P.in[I_SLRU][(size_t)(l * 128 + ((t0 + 16 * q - NPT) >> 2) + (i >> 2)) * 1024 + cgs];
;                 if (reset) { A = 0.f; B = a2 * h0 + b2; } else { A *= a2; B = a2 * B + b2; }
.LBB0_1105:
	s_cmpk_lt_u32 s42, 0x10a
	s_cselect_b64 s[4:5], -1, 0
	s_cmp_gt_i32 s12, -1
	s_cselect_b64 s[54:55], -1, 0
	s_or_b64 s[0:1], s[54:55], s[4:5]
	v_cndmask_b32_e64 v0, 0, 1, s[0:1]
	v_cmp_ne_u32_e64 s[46:47], 1, v0
	s_andn2_b64 vcc, exec, s[0:1]
	s_cbranch_vccnz .LBB0_1113
	v_cndmask_b32_e64 v0, 0, 1, s[4:5]
	v_cmp_ne_u32_e64 s[48:49], 1, v0
	s_andn2_b64 vcc, exec, s[4:5]
	s_lshl_b32 s43, s42, 6
	s_cbranch_vccnz .LBB0_1159
	ds_read_b128 v[0:3], v182
	ds_read_b128 v[4:7], v182 offset:16
	ds_read_b128 v[8:11], v183
	ds_read_b128 v[12:15], v183 offset:16
	ds_read_b128 v[24:27], v183 offset:512
	ds_read_b128 v[28:31], v183 offset:528
	s_waitcnt vmcnt(2)
	s_cmpk_gt_u32 s43, 0x407f
	s_cbranch_scc0 .Lh0_none
	v_add_u32_e32 v220, s43, v191
	v_ashrrev_i32_e32 v220, 2, v220
	v_add_u32_e32 v220, s40, v220
	v_ashrrev_i32_e32 v221, 31, v220
	v_lshlrev_b64 v[220:221], 12, v[220:221]
	s_mov_b64 s[74:75], 0x1000
	v_lshl_add_u64 v[220:221], v[170:171], 0, v[220:221]
	global_load_dword v217, v[220:221], off
	v_lshl_add_u64 v[220:221], v[220:221], 0, s[74:75]
	global_load_dword v218, v[220:221], off
	v_lshl_add_u64 v[220:221], v[220:221], 0, s[74:75]
	global_load_dword v219, v[220:221], off
	v_lshl_add_u64 v[220:221], v[220:221], 0, s[74:75]
	global_load_dword v222, v[220:221], off
.Lh0_none:
	v_lshlrev_b32_e32 v16, 16, v120
	v_and_b32_e32 v17, 0xffff0000, v120
	v_lshlrev_b32_e32 v18, 16, v121
	v_and_b32_e32 v19, 0xffff0000, v121
	v_lshlrev_b32_e32 v20, 16, v122
	v_and_b32_e32 v21, 0xffff0000, v122
	v_lshlrev_b32_e32 v22, 16, v123
	v_and_b32_e32 v23, 0xffff0000, v123
	s_waitcnt lgkmcnt(2)
	v_pk_fma_f32 v[8:9], v[8:9], v[16:17], v[0:1]
	v_pk_fma_f32 v[10:11], v[10:11], v[18:19], v[2:3]
	v_pk_fma_f32 v[12:13], v[12:13], v[20:21], v[4:5]
	v_pk_fma_f32 v[14:15], v[14:15], v[22:23], v[6:7]
	ds_read_b128 v[0:3], v183 offset:1024
	ds_read_b128 v[4:7], v183 offset:1040
	v_lshlrev_b32_e32 v16, 16, v124
	v_and_b32_e32 v17, 0xffff0000, v124
	v_lshlrev_b32_e32 v18, 16, v125
	v_and_b32_e32 v19, 0xffff0000, v125
	v_lshlrev_b32_e32 v20, 16, v126
	v_and_b32_e32 v21, 0xffff0000, v126
	v_lshlrev_b32_e32 v22, 16, v127
	v_and_b32_e32 v23, 0xffff0000, v127
	s_waitcnt lgkmcnt(2)
	v_pk_fma_f32 v[10:11], v[26:27], v[18:19], v[10:11]
	v_pk_fma_f32 v[8:9], v[24:25], v[16:17], v[8:9]
	v_pk_fma_f32 v[14:15], v[30:31], v[22:23], v[14:15]
	v_pk_fma_f32 v[12:13], v[28:29], v[20:21], v[12:13]
	ds_read_b128 v[24:27], v183 offset:1536
	ds_read_b128 v[28:31], v183 offset:1552
	v_lshlrev_b32_e32 v16, 16, v128
	v_and_b32_e32 v17, 0xffff0000, v128
	v_lshlrev_b32_e32 v18, 16, v129
	v_and_b32_e32 v19, 0xffff0000, v129
	v_lshlrev_b32_e32 v20, 16, v130
	v_and_b32_e32 v21, 0xffff0000, v130
	v_lshlrev_b32_e32 v22, 16, v131
	v_and_b32_e32 v23, 0xffff0000, v131
	s_waitcnt lgkmcnt(2)
	v_pk_fma_f32 v[8:9], v[0:1], v[16:17], v[8:9]
	v_pk_fma_f32 v[10:11], v[2:3], v[18:19], v[10:11]
	v_pk_fma_f32 v[12:13], v[4:5], v[20:21], v[12:13]
	v_pk_fma_f32 v[14:15], v[6:7], v[22:23], v[14:15]
	v_lshlrev_b32_e32 v16, 16, v132
	v_and_b32_e32 v17, 0xffff0000, v132
	v_lshlrev_b32_e32 v18, 16, v133
	v_and_b32_e32 v19, 0xffff0000, v133
	v_lshlrev_b32_e32 v20, 16, v134
	v_and_b32_e32 v21, 0xffff0000, v134
	v_lshlrev_b32_e32 v22, 16, v135
	v_and_b32_e32 v23, 0xffff0000, v135
	s_waitcnt lgkmcnt(0)
	v_pk_fma_f32 v[2:3], v[26:27], v[18:19], v[10:11]
	v_pk_fma_f32 v[0:1], v[24:25], v[16:17], v[8:9]
	v_pk_fma_f32 v[6:7], v[30:31], v[22:23], v[14:15]
	v_pk_fma_f32 v[4:5], v[28:29], v[20:21], v[12:13]
	v_cvt_pk_bf16_f32 v0, v0, v1
	v_cvt_pk_bf16_f32 v1, v2, v3
	v_cvt_pk_bf16_f32 v2, v4, v5
	v_cvt_pk_bf16_f32 v3, v6, v7
	ds_write_b128 v238, v[0:3]
	ds_read_b128 v[0:3], v182
	ds_read_b128 v[4:7], v182 offset:16
	ds_read_b128 v[8:11], v183
	ds_read_b128 v[12:15], v183 offset:16
	ds_read_b128 v[24:27], v183 offset:512
	ds_read_b128 v[28:31], v183 offset:528
	v_lshlrev_b32_e32 v16, 16, v136
	v_and_b32_e32 v17, 0xffff0000, v136
	v_lshlrev_b32_e32 v18, 16, v137
	v_and_b32_e32 v19, 0xffff0000, v137
	v_lshlrev_b32_e32 v20, 16, v138
	v_and_b32_e32 v21, 0xffff0000, v138
	v_lshlrev_b32_e32 v22, 16, v139
	v_and_b32_e32 v23, 0xffff0000, v139
	s_waitcnt lgkmcnt(2)
	v_pk_fma_f32 v[8:9], v[8:9], v[16:17], v[0:1]
	v_pk_fma_f32 v[10:11], v[10:11], v[18:19], v[2:3]
	v_pk_fma_f32 v[12:13], v[12:13], v[20:21], v[4:5]
	v_pk_fma_f32 v[14:15], v[14:15], v[22:23], v[6:7]
	ds_read_b128 v[0:3], v183 offset:1024
	ds_read_b128 v[4:7], v183 offset:1040
	v_lshlrev_b32_e32 v16, 16, v140
	v_and_b32_e32 v17, 0xffff0000, v140
	v_lshlrev_b32_e32 v18, 16, v141
	v_and_b32_e32 v19, 0xffff0000, v141
	v_lshlrev_b32_e32 v20, 16, v142
	v_and_b32_e32 v21, 0xffff0000, v142
	v_lshlrev_b32_e32 v22, 16, v143
	v_and_b32_e32 v23, 0xffff0000, v143
	s_waitcnt lgkmcnt(2)
	v_pk_fma_f32 v[10:11], v[26:27], v[18:19], v[10:11]
	v_pk_fma_f32 v[8:9], v[24:25], v[16:17], v[8:9]
	v_pk_fma_f32 v[14:15], v[30:31], v[22:23], v[14:15]
	v_pk_fma_f32 v[12:13], v[28:29], v[20:21], v[12:13]
	ds_read_b128 v[24:27], v183 offset:1536
	ds_read_b128 v[28:31], v183 offset:1552
	v_lshlrev_b32_e32 v16, 16, v144
	v_and_b32_e32 v17, 0xffff0000, v144
	v_lshlrev_b32_e32 v18, 16, v145
	v_and_b32_e32 v19, 0xffff0000, v145
	v_lshlrev_b32_e32 v20, 16, v146
	v_and_b32_e32 v21, 0xffff0000, v146
	v_lshlrev_b32_e32 v22, 16, v147
	v_and_b32_e32 v23, 0xffff0000, v147
	s_waitcnt lgkmcnt(2)
	v_pk_fma_f32 v[8:9], v[0:1], v[16:17], v[8:9]
	v_pk_fma_f32 v[10:11], v[2:3], v[18:19], v[10:11]
	v_pk_fma_f32 v[12:13], v[4:5], v[20:21], v[12:13]
	v_pk_fma_f32 v[14:15], v[6:7], v[22:23], v[14:15]
	v_lshlrev_b32_e32 v16, 16, v148
	v_and_b32_e32 v17, 0xffff0000, v148
	v_lshlrev_b32_e32 v18, 16, v149
	v_and_b32_e32 v19, 0xffff0000, v149
	v_lshlrev_b32_e32 v20, 16, v150
	v_and_b32_e32 v21, 0xffff0000, v150
	v_lshlrev_b32_e32 v22, 16, v151
	v_and_b32_e32 v23, 0xffff0000, v151
	s_waitcnt lgkmcnt(0)
	v_pk_fma_f32 v[2:3], v[26:27], v[18:19], v[10:11]
	v_pk_fma_f32 v[0:1], v[24:25], v[16:17], v[8:9]
	v_pk_fma_f32 v[6:7], v[30:31], v[22:23], v[14:15]
	v_pk_fma_f32 v[4:5], v[28:29], v[20:21], v[12:13]
	v_cvt_pk_bf16_f32 v0, v0, v1
	v_cvt_pk_bf16_f32 v1, v2, v3
	v_cvt_pk_bf16_f32 v2, v4, v5
	v_cvt_pk_bf16_f32 v3, v6, v7
	v_readlane_b32 s0, v255, 32
	s_nop 0
	s_add_i32 s0, s42, s0
	s_cmpk_gt_u32 s0, 0x109
	ds_write_b128 v238, v[0:3] offset:8704
	s_cbranch_scc1 .LBB0_1158
	s_mov_b64 s[88:89], 0
	s_mov_b64 s[90:91], 0
	s_mov_b64 s[92:93], 0
	s_mov_b64 s[60:61], 0
	s_mov_b64 s[62:63], 0
	s_mov_b64 s[66:67], 0
	v_lshl_add_u32 v0, s0, 6, v177
	v_mul_hi_i32 v1, v0, s71
	v_lshrrev_b32_e32 v2, 31, v1
	v_ashrrev_i32_e32 v1, 7, v1
	v_add_u32_e32 v1, v1, v2
	s_cmpk_gt_u32 s0, 0x101
	v_mul_lo_u32 v1, v1, s73
	v_sub_u32_e32 v1, v0, v1
	s_cselect_b64 s[52:53], -1, 0
	v_cndmask_b32_e64 v4, v1, v154, s[52:53]
	v_cmp_lt_i32_e32 vcc, -1, v4
	v_ashrrev_i32_e32 v1, 31, v0
	s_and_saveexec_b64 s[0:1], vcc
	s_xor_b64 s[0:1], exec, s[0:1]
	s_cbranch_execz .LBB0_1110
	v_lshlrev_b64 v[2:3], 11, v[0:1]
	v_lshl_add_u64 v[2:3], v[168:169], 0, v[2:3]
	global_load_dwordx4 v[120:123], v[2:3], off

; template <int MODE> __device__ __forceinline__ void lru_phase(const Params& P, LAS unsigned char* lds, int l, int tid_in) {
;     ...
;             for (int i = 0; i < 16; ++i) {
;                 const float a2 = sa[(16 * q + i) * 128 + cs], b2 = sb[(16 * q + i) * 128 + cs];
;                 const bool reset = samp ? ((i & 3) == 0) : (i == rs);
;                 float h0 = 0.f; if (samp && reset) h0 = P.in[I_SLRU][(size_t)(l * 128 + ((t0 + 16 * q - NPT) >> 2) + (i >> 2)) * 1024 + cgs];
;                 if (reset) { A = 0.f; B = a2 * h0 + b2; } else { A *= a2; B = a2 * B + b2; }
;             }
.LBB0_1191:
	ds_read2st64_b32 v[4:5], v22 offset0:70 offset1:72
	ds_read2st64_b32 v[8:9], v22 offset0:198 offset1:200
	ds_read2st64_b32 v[6:7], v22 offset0:74 offset1:76
	ds_read2st64_b32 v[12:13], v22 offset0:202 offset1:204
	s_and_b64 vcc, exec, s[52:53]
	s_cbranch_vccnz .LBB0_1193
	s_waitcnt lgkmcnt(2)
	v_or_b32_e32 v8, 1, v2
	v_ashrrev_i32_e32 v9, 31, v8
	v_lshlrev_b64 v[8:9], 12, v[8:9]
	v_lshl_add_u64 v[8:9], v[170:171], 0, v[8:9]
	s_branch .LBB0_1194

; template <int MODE> __device__ __forceinline__ void lru_phase(const Params& P, LAS unsigned char* lds, int l, int tid_in) {
;     ...
;             for (int i = 0; i < 16; ++i) {
;                 const float a2 = sa[(16 * q + i) * 128 + cs], b2 = sb[(16 * q + i) * 128 + cs];
;                 const bool reset = samp ? ((i & 3) == 0) : (i == rs);
;                 float h0 = 0.f; if (samp && reset) h0 = P.in[I_SLRU][(size_t)(l * 128 + ((t0 + 16 * q - NPT) >> 2) + (i >> 2)) * 1024 + cgs];
;                 if (reset) { A = 0.f; B = a2 * h0 + b2; } else { A *= a2; B = a2 * B + b2; }
;             }
.LBB0_1194:
	ds_read2st64_b32 v[8:9], v22 offset0:78 offset1:80
	ds_read2st64_b32 v[14:15], v22 offset0:206 offset1:208
	ds_read2st64_b32 v[10:11], v22 offset0:82 offset1:84
	ds_read2st64_b32 v[18:19], v22 offset0:210 offset1:212
	s_and_b64 vcc, exec, s[52:53]
	s_cbranch_vccnz .LBB0_1196
	s_waitcnt lgkmcnt(4)
	v_or_b32_e32 v12, 2, v2
	v_ashrrev_i32_e32 v13, 31, v12
	v_lshlrev_b64 v[12:13], 12, v[12:13]
	v_lshl_add_u64 v[12:13], v[170:171], 0, v[12:13]
	s_branch .LBB0_1197

; template <int MODE> __device__ __forceinline__ void lru_phase(const Params& P, LAS unsigned char* lds, int l, int tid_in) {
;     ...
;             for (int i = 0; i < 16; ++i) {
;                 const float a2 = sa[(16 * q + i) * 128 + cs], b2 = sb[(16 * q + i) * 128 + cs];
;                 const bool reset = samp ? ((i & 3) == 0) : (i == rs);
;                 float h0 = 0.f; if (samp && reset) h0 = P.in[I_SLRU][(size_t)(l * 128 + ((t0 + 16 * q - NPT) >> 2) + (i >> 2)) * 1024 + cgs];
;                 if (reset) { A = 0.f; B = a2 * h0 + b2; } else { A *= a2; B = a2 * B + b2; }
;             }
.LBB0_1197:
	ds_read2st64_b32 v[16:17], v22 offset0:86 offset1:88
	ds_read2st64_b32 v[20:21], v22 offset0:214 offset1:216
	s_waitcnt lgkmcnt(4)
	ds_read2st64_b32 v[14:15], v22 offset0:90 offset1:92
	ds_read2st64_b32 v[12:13], v22 offset0:218 offset1:220
	s_and_b64 vcc, exec, s[52:53]
	s_cbranch_vccnz .LBB0_1199
	v_or_b32_e32 v2, 3, v2
	s_waitcnt vmcnt(2)
	v_ashrrev_i32_e32 v3, 31, v2
	v_lshlrev_b64 v[2:3], 12, v[2:3]
	v_lshl_add_u64 v[2:3], v[170:171], 0, v[2:3]
	s_waitcnt vmcnt(0)
	v_mov_b32_e32 v1, v222
	s_branch .LBB0_1200

; template <int MODE> __device__ __forceinline__ void lru_phase(const Params& P, LAS unsigned char* lds, int l, int tid_in) {
;     ...
;         if (prev >= 0) {
;             const int pos0 = psamp ? 0 : ((pt0 + 16 * q) % LP);
;             const int rs = psamp ? -1 : (pos0 == 0 ? 0 : (LP - pos0 < 16 ? LP - pos0 : -1));
;             float hh = 0.f;
; #pragma unroll
;             for (int r = 0; r < 4; ++r) hh = fa[r * 128 + cs] * hh + fb[r * 128 + cs];
; #pragma unroll
;             for (int j = 0; j < 3; ++j) if (j < q) hh = pqa[j] * hh + pqb[j];
; #pragma unroll
;             for (int i = 0; i < 16; ++i) {
;                 const float a2 = psa[(16 * q + i) * 128 + cs], b2 = psb[(16 * q + i) * 128 + cs];
;                 const bool reset = psamp ? ((i & 3) == 0) : (i == rs);
;                 float h0 = 0.f; if (psamp && reset) h0 = P.in[I_SLRU][(size_t)(l * 128 + ((pt0 + 16 * q - NPT) >> 2) + (i >> 2)) * 1024 + cgs];
;                 hh = reset ? a2 * h0 + b2 : a2 * hh + b2;
;                 psb[(16 * q + i) * 128 + cs] = hh;
;             }
.LBB0_1204:
	v_lshl_add_u32 v6, v206, 2, s12
	ds_read2st64_b32 v[2:3], v6 offset0:68 offset1:196
	ds_read2st64_b32 v[22:23], v6 offset0:70 offset1:72
	ds_read2st64_b32 v[24:25], v6 offset0:198 offset1:200
	ds_read2st64_b32 v[26:27], v6 offset0:74 offset1:76
	ds_read2st64_b32 v[28:29], v6 offset0:202 offset1:204
	ds_read2st64_b32 v[30:31], v6 offset0:78 offset1:80
	ds_read2st64_b32 v[82:83], v6 offset0:206 offset1:208
	ds_read2st64_b32 v[84:85], v6 offset0:82 offset1:84
	ds_read2st64_b32 v[86:87], v6 offset0:210 offset1:212
	ds_read2st64_b32 v[186:187], v6 offset0:86 offset1:88
	ds_read2st64_b32 v[188:189], v6 offset0:214 offset1:216
	ds_read2st64_b32 v[226:227], v6 offset0:90 offset1:92
	ds_read2st64_b32 v[228:229], v6 offset0:218 offset1:220
	ds_read2st64_b32 v[242:243], v6 offset0:94 offset1:96
	ds_read2st64_b32 v[244:245], v6 offset0:98 offset1:222
	ds_read2st64_b32 v[246:247], v6 offset0:224 offset1:226
	ds_read_b32 v9, v207
	ds_read_b32 v4, v208
	ds_read_b32 v10, v209
	ds_read_b32 v5, v210
	ds_read_b32 v11, v211
	ds_read_b32 v7, v212
	ds_read_b32 v12, v213
	ds_read_b32 v8, v214
	v_add_u32_e32 v0, s44, v191
	v_ashrrev_i32_e32 v0, 2, v0
	v_cndmask_b32_e64 v1, 0, 1, s[82:83]
	v_add_u32_e32 v0, s40, v0
	v_cmp_ne_u32_e64 s[54:55], 1, v1
	s_andn2_b64 vcc, exec, s[82:83]
	v_mov_b32_e32 v1, 0
	s_cbranch_vccnz .LBB0_1206
	v_mov_b32_e32 v1, v217
.LBB0_1206:
	s_waitcnt lgkmcnt(6)
	v_fmac_f32_e32 v4, 0, v9
	s_waitcnt lgkmcnt(4)
	v_fmac_f32_e32 v5, v4, v10
	s_waitcnt lgkmcnt(2)
	v_fmac_f32_e32 v7, v5, v11
	s_waitcnt lgkmcnt(0)
	v_fmac_f32_e32 v8, v7, v12
	v_fma_f32 v4, v172, v8, v157
	v_cndmask_b32_e64 v4, v8, v4, s[36:37]
	v_fma_f32 v5, v173, v4, v174
	v_cndmask_b32_e64 v4, v4, v5, s[30:31]
	v_fma_f32 v5, v156, v4, v175
	v_cndmask_b32_e64 v4, v4, v5, s[20:21]
	s_waitcnt vmcnt(0)
	v_cndmask_b32_e64 v1, v4, v1, s[0:1]
	v_fmac_f32_e32 v3, v2, v1
	v_fma_f32 v1, v22, v3, v24
	ds_write2st64_b32 v6, v3, v1 offset0:196 offset1:198
	v_fmac_f32_e32 v25, v23, v1
	v_fma_f32 v1, v25, v26, v28
	ds_write2st64_b32 v6, v25, v1 offset0:200 offset1:202
	v_cndmask_b32_e64 v1, v218, v1, s[54:55]
	v_fmac_f32_e32 v29, v27, v1
	v_fma_f32 v1, v30, v29, v82
	ds_write2st64_b32 v6, v29, v1 offset0:204 offset1:206
	v_fmac_f32_e32 v83, v31, v1
	v_fma_f32 v1, v83, v84, v86
	ds_write2st64_b32 v6, v83, v1 offset0:208 offset1:210
	v_cndmask_b32_e64 v1, v219, v1, s[54:55]
	v_fmac_f32_e32 v87, v85, v1
	v_fma_f32 v1, v186, v87, v188
	ds_write2st64_b32 v6, v87, v1 offset0:212 offset1:214
	v_fmac_f32_e32 v189, v187, v1
	v_fma_f32 v1, v189, v226, v228
	ds_write2st64_b32 v6, v189, v1 offset0:216 offset1:218
	v_cndmask_b32_e64 v1, v222, v1, s[54:55]
	v_fmac_f32_e32 v229, v227, v1
	v_fma_f32 v0, v242, v229, v245
	ds_write2st64_b32 v6, v229, v0 offset0:220 offset1:222
	v_fma_f32 v0, v0, v243, v246
	v_fmac_f32_e32 v247, v0, v244
	ds_write2st64_b32 v6, v0, v247 offset0:224 offset1:226
